# GEMM prologue: second K-tile LDS-DMA loads issued before the first wait (vmcnt(2)->vmcnt(8)), one cold latency less per GEMM call
# speedup vs baseline: 1.0194x; 1.0021x over previous
.LBB0_424:
	s_add_i32 s24, s14, 0x18000
	s_mov_b64 s[76:77], 0x80
	v_lshl_add_u64 v[6:7], v[6:7], 0, s[76:77]
	s_mov_b32 m0, s24
	s_add_i32 s25, s14, 0x1a000
	global_load_lds_dwordx4 v[6:7], off
	v_lshl_add_u64 v[4:5], v[4:5], 0, s[76:77]
	s_mov_b32 m0, s25
	s_add_i32 s26, s14, 0x8000
	global_load_lds_dwordx4 v[4:5], off
	v_lshl_add_u64 v[4:5], v[8:9], 0, s[76:77]
	s_mov_b32 m0, s26
	s_add_i32 s27, s14, 0xa000
	global_load_lds_dwordx4 v[4:5], off
	v_lshl_add_u64 v[4:5], v[10:11], 0, s[76:77]
	s_mov_b32 m0, s27
	s_add_i32 s28, s14, 0x1c000
	global_load_lds_dwordx4 v[4:5], off
	v_lshl_add_u64 v[2:3], v[2:3], 0, s[76:77]
	s_mov_b32 m0, s28
	s_add_i32 s29, s14, 0x1e000
	global_load_lds_dwordx4 v[2:3], off
	v_lshl_add_u64 v[0:1], v[0:1], 0, s[76:77]
	s_mov_b32 m0, s29
	s_sext_i32_i8 s81, s0
	global_load_lds_dwordx4 v[0:1], off
	s_ashr_i32 s0, s3, 31
	v_bfe_u32 v145, v12, 4, 2
	s_lshr_b32 s0, s0, 26
	v_and_b32_e32 v144, 15, v12
	s_add_i32 s0, s3, s0
	v_lshlrev_b32_e32 v0, 4, v145
	v_lshlrev_b32_e32 v1, 2, v12
	s_ashr_i32 s30, s0, 6
	v_lshl_or_b32 v0, v144, 6, v0
	s_lshl_b32 s0, s34, 13
	v_and_b32_e32 v1, 32, v1
	v_bitop3_b32 v146, v0, s0, v1 bitop3:0xde
	s_lshl_b32 s0, s33, 5
	s_and_b32 s0, s0, 0x60
	s_lshl_b32 s4, s0, 7
	v_bitop3_b32 v2, v0, s4, v1 bitop3:0xde
	v_add_u32_e32 v0, v18, v16
	s_lshl_b32 s31, s34, 6
	v_add_lshl_u32 v0, v0, v17, 1
	v_mov_b32_e32 v1, v133
	s_cmp_gt_i32 s3, 63
	v_lshl_add_u64 v[136:137], s[8:9], 0, v[0:1]
	v_add_u32_e32 v0, v15, v13
	s_waitcnt vmcnt(8)
	s_mov_b32 s99, 0
	s_barrier
	s_waitcnt vmcnt(6)
	s_cselect_b64 s[4:5], -1, 0
	s_add_i32 s33, s30, -2
	v_readlane_b32 s6, v246, 5
	v_add_lshl_u32 v0, v0, v14, 1
	s_cmpk_lt_u32 s1, 0x100
	v_readlane_b32 s7, v246, 6
	v_lshl_add_u64 v[138:139], s[8:9], 0, v[0:1]
	v_cndmask_b32_e64 v0, 0, 1, s[4:5]
	s_cselect_b64 s[78:79], -1, 0
	s_ashr_i32 s34, s31, 31
	s_ashr_i32 s35, s6, 31
	s_mov_b32 s68, s6
	v_mov_b64_e32 v[140:141], 0xc60
	v_mov_b64_e32 v[142:143], 0xc5f
	v_cmp_ne_u32_e64 s[6:7], 1, v0
	v_or_b32_e32 v147, 0x10000, v2
	v_add_u32_e32 v148, 0x10400, v2
	v_add_u32_e32 v149, 0x10800, v2
	v_add_u32_e32 v150, 0x10c00, v2
	v_or_b32_e32 v151, 0x14000, v2
	v_add_u32_e32 v152, 0x14400, v2
	v_add_u32_e32 v153, 0x14800, v2
	v_add_u32_e32 v154, 0x14c00, v2
	s_add_i32 s69, s14, 0xc000
	s_add_i32 s72, s14, 0xe000
	v_or_b32_e32 v155, 0x18000, v2
	v_add_u32_e32 v156, 0x18400, v2
	v_add_u32_e32 v157, 0x18800, v2
	v_add_u32_e32 v158, 0x18c00, v2
	v_or_b32_e32 v159, 0x1c000, v2
	v_add_u32_e32 v160, 0x1c400, v2
	v_add_u32_e32 v161, 0x1c800, v2
	v_add_u32_e32 v163, 0x1cc00, v2
	s_movk_i32 s73, 0x1600
	s_lshl_b32 s70, s0, 1
	s_mov_b32 s80, s71
	s_barrier
	s_branch .LBB0_427

.LBB0_822:
	s_add_i32 s33, s18, 0x18000
	s_mov_b64 s[26:27], 0x80
	v_lshl_add_u64 v[10:11], v[10:11], 0, s[26:27]
	s_mov_b32 m0, s33
	s_add_i32 s34, s18, 0x1a000
	global_load_lds_dwordx4 v[10:11], off
	v_lshl_add_u64 v[4:5], v[4:5], 0, s[26:27]
	s_mov_b32 m0, s34
	s_add_i32 s35, s18, 0x8000
	global_load_lds_dwordx4 v[4:5], off
	v_lshl_add_u64 v[4:5], v[6:7], 0, s[26:27]
	s_mov_b32 m0, s35
	s_add_i32 s68, s18, 0xa000
	global_load_lds_dwordx4 v[4:5], off
	v_lshl_add_u64 v[4:5], v[8:9], 0, s[26:27]
	s_mov_b32 m0, s68
	s_add_i32 s69, s18, 0x1c000
	global_load_lds_dwordx4 v[4:5], off
	v_lshl_add_u64 v[2:3], v[2:3], 0, s[26:27]
	s_mov_b32 m0, s69
	s_add_i32 s72, s18, 0x1e000
	global_load_lds_dwordx4 v[2:3], off
	v_lshl_add_u64 v[0:1], v[0:1], 0, s[26:27]
	s_mov_b32 m0, s72
	s_ashr_i32 s0, s36, 31
	global_load_lds_dwordx4 v[0:1], off
	v_bfe_u32 v147, v12, 4, 2
	s_lshr_b32 s0, s0, 26
	v_and_b32_e32 v146, 15, v12
	s_add_i32 s0, s36, s0
	v_lshlrev_b32_e32 v0, 4, v147
	v_lshlrev_b32_e32 v1, 2, v12
	s_ashr_i32 s73, s0, 6
	v_lshl_or_b32 v0, v146, 6, v0
	s_lshl_b32 s0, s6, 13
	v_and_b32_e32 v1, 32, v1
	v_bitop3_b32 v148, v0, s0, v1 bitop3:0xde
	s_lshl_b32 s0, s7, 5
	s_lshl_b32 s78, s6, 6
	s_and_b32 s6, s0, 0x60
	s_lshl_b32 s0, s6, 7
	v_bitop3_b32 v2, v0, s0, v1 bitop3:0xde
	v_add_u32_e32 v0, v15, v13
	v_add_lshl_u32 v0, v0, v14, 1
	v_mov_b32_e32 v1, v131
	s_cmp_gt_i32 s36, 63
	v_lshl_add_u64 v[136:137], s[10:11], 0, v[0:1]
	v_add_u32_e32 v0, v18, v16
	s_cselect_b64 s[0:1], -1, 0
	s_add_i32 s79, s73, -2
	v_readlane_b32 s4, v246, 5
	v_add_lshl_u32 v0, v0, v17, 1
	s_waitcnt vmcnt(8)
	s_mov_b32 s99, 0
	s_barrier
	s_waitcnt vmcnt(6)
	s_cmpk_lt_u32 s3, 0x100
	v_readlane_b32 s5, v246, 6
	v_lshl_add_u64 v[138:139], s[10:11], 0, v[0:1]
	v_cndmask_b32_e64 v0, 0, 1, s[0:1]
	s_cselect_b64 s[36:37], -1, 0
	s_mov_b32 s47, 0
	s_ashr_i32 s81, s4, 31
	s_mov_b32 s82, s4
	v_cmp_ne_u32_e64 s[4:5], 1, v0
	v_mbcnt_lo_u32_b32 v0, -1, 0
	s_ashr_i32 s80, s78, 31
	s_ashr_i32 s83, s2, 31
	v_mov_b64_e32 v[140:141], 0x200
	v_mov_b64_e32 v[142:143], 0x1ff
	v_or_b32_e32 v149, 0x10000, v2
	v_add_u32_e32 v150, 0x10400, v2
	v_add_u32_e32 v151, 0x10800, v2
	v_add_u32_e32 v152, 0x10c00, v2
	v_or_b32_e32 v153, 0x14000, v2
	v_add_u32_e32 v154, 0x14400, v2
	v_add_u32_e32 v155, 0x14800, v2
	v_add_u32_e32 v156, 0x14c00, v2
	s_add_i32 s90, s18, 0xc000
	s_add_i32 s91, s18, 0xe000
	v_or_b32_e32 v157, 0x18000, v2
	v_add_u32_e32 v158, 0x18400, v2
	v_add_u32_e32 v159, 0x18800, v2
	v_add_u32_e32 v160, 0x18c00, v2
	v_or_b32_e32 v161, 0x1c000, v2
	v_add_u32_e32 v163, 0x1c400, v2
	v_add_u32_e32 v164, 0x1c800, v2
	v_add_u32_e32 v165, 0x1cc00, v2
	v_mbcnt_hi_u32_b32 v166, -1, v0
	s_lshl_b32 s46, s6, 1
	s_mov_b32 s92, s47
	s_barrier
	s_branch .LBB0_825

.LBB0_863:
	s_add_i32 s34, s7, 0x18000
	s_mov_b64 s[16:17], 0x80
	v_lshl_add_u64 v[10:11], v[10:11], 0, s[16:17]
	s_mov_b32 m0, s34
	s_add_i32 s35, s7, 0x1a000
	global_load_lds_dwordx4 v[10:11], off
	v_lshl_add_u64 v[6:7], v[6:7], 0, s[16:17]
	s_mov_b32 m0, s35
	s_add_i32 s36, s7, 0x8000
	global_load_lds_dwordx4 v[6:7], off
	v_lshl_add_u64 v[6:7], v[8:9], 0, s[16:17]
	s_mov_b32 m0, s36
	s_add_i32 s37, s7, 0xa000
	global_load_lds_dwordx4 v[6:7], off
	v_lshl_add_u64 v[4:5], v[4:5], 0, s[16:17]
	s_mov_b32 m0, s37
	s_add_i32 s46, s7, 0x1c000
	global_load_lds_dwordx4 v[4:5], off
	v_lshl_add_u64 v[2:3], v[2:3], 0, s[16:17]
	s_mov_b32 m0, s46
	s_add_i32 s47, s7, 0x1e000
	global_load_lds_dwordx4 v[2:3], off
	v_lshl_add_u64 v[0:1], v[0:1], 0, s[16:17]
	s_mov_b32 m0, s47
	s_lshl_b32 s3, s3, 5
	global_load_lds_dwordx4 v[0:1], off
	s_waitcnt vmcnt(8)
	s_mov_b32 s99, 0
	s_barrier
	s_waitcnt vmcnt(6)
	s_lshl_b32 s6, s70, 6
	s_and_b32 s3, s3, 0x60
	s_mov_b32 s5, 0
	v_and_b32_e32 v130, 15, v12
	v_bfe_u32 v142, v12, 4, 2
	s_cmp_lt_i32 s27, 64
	v_mov_b32_e32 v126, 0
	v_mov_b32_e32 v125, 0
	v_mov_b32_e32 v124, 0
	v_mov_b32_e32 v123, 0
	v_mov_b32_e32 v122, 0
	v_mov_b32_e32 v121, 0
	v_mov_b32_e32 v120, 0
	v_mov_b32_e32 v111, 0
	v_mov_b32_e32 v110, 0
	v_mov_b32_e32 v109, 0
	v_mov_b32_e32 v108, 0
	v_mov_b32_e32 v107, 0
	v_mov_b32_e32 v106, 0
	v_mov_b32_e32 v105, 0
	v_mov_b32_e32 v104, 0
	v_mov_b32_e32 v95, 0
	v_mov_b32_e32 v94, 0
	v_mov_b32_e32 v93, 0
	v_mov_b32_e32 v92, 0
	v_mov_b32_e32 v91, 0
	v_mov_b32_e32 v90, 0
	v_mov_b32_e32 v89, 0
	v_mov_b32_e32 v88, 0
	v_mov_b32_e32 v79, 0
	v_mov_b32_e32 v78, 0
	v_mov_b32_e32 v77, 0
	v_mov_b32_e32 v76, 0
	v_mov_b32_e32 v75, 0
	v_mov_b32_e32 v74, 0
	v_mov_b32_e32 v73, 0
	v_mov_b32_e32 v72, 0
	v_mov_b32_e32 v119, 0
	v_mov_b32_e32 v118, 0
	v_mov_b32_e32 v117, 0
	v_mov_b32_e32 v116, 0
	v_mov_b32_e32 v115, 0
	v_mov_b32_e32 v114, 0
	v_mov_b32_e32 v113, 0
	v_mov_b32_e32 v112, 0
	v_mov_b32_e32 v103, 0
	v_mov_b32_e32 v102, 0
	v_mov_b32_e32 v101, 0
	v_mov_b32_e32 v100, 0
	v_mov_b32_e32 v99, 0
	v_mov_b32_e32 v98, 0
	v_mov_b32_e32 v97, 0
	v_mov_b32_e32 v96, 0
	v_mov_b32_e32 v87, 0
	v_mov_b32_e32 v86, 0
	v_mov_b32_e32 v85, 0
	v_mov_b32_e32 v84, 0
	v_mov_b32_e32 v83, 0
	v_mov_b32_e32 v82, 0
	v_mov_b32_e32 v81, 0
	v_mov_b32_e32 v80, 0
	v_mov_b32_e32 v71, 0
	v_mov_b32_e32 v70, 0
	v_mov_b32_e32 v69, 0
	v_mov_b32_e32 v68, 0
	v_mov_b32_e32 v67, 0
	v_mov_b32_e32 v66, 0
	v_mov_b32_e32 v65, 0
	v_mov_b32_e32 v64, 0
	v_mov_b32_e32 v63, 0
	v_mov_b32_e32 v62, 0
	v_mov_b32_e32 v61, 0
	v_mov_b32_e32 v60, 0
	v_mov_b32_e32 v59, 0
	v_mov_b32_e32 v58, 0
	v_mov_b32_e32 v57, 0
	v_mov_b32_e32 v56, 0
	v_mov_b32_e32 v47, 0
	v_mov_b32_e32 v46, 0
	v_mov_b32_e32 v45, 0
	v_mov_b32_e32 v44, 0
	v_mov_b32_e32 v43, 0
	v_mov_b32_e32 v42, 0
	v_mov_b32_e32 v41, 0
	v_mov_b32_e32 v40, 0
	v_mov_b32_e32 v31, 0
	v_mov_b32_e32 v30, 0
	v_mov_b32_e32 v29, 0
	v_mov_b32_e32 v28, 0
	v_mov_b32_e32 v27, 0
	v_mov_b32_e32 v26, 0
	v_mov_b32_e32 v25, 0
	v_mov_b32_e32 v24, 0
	v_mov_b32_e32 v15, 0
	v_mov_b32_e32 v14, 0
	v_mov_b32_e32 v13, 0
	v_mov_b32_e32 v12, 0
	v_mov_b32_e32 v11, 0
	v_mov_b32_e32 v10, 0
	v_mov_b32_e32 v9, 0
	v_mov_b32_e32 v8, 0
	v_mov_b32_e32 v55, 0
	v_mov_b32_e32 v54, 0
	v_mov_b32_e32 v53, 0
	v_mov_b32_e32 v52, 0
	v_mov_b32_e32 v51, 0
	v_mov_b32_e32 v50, 0
	v_mov_b32_e32 v49, 0
	v_mov_b32_e32 v48, 0
	v_mov_b32_e32 v39, 0
	v_mov_b32_e32 v38, 0
	v_mov_b32_e32 v37, 0
	v_mov_b32_e32 v36, 0
	v_mov_b32_e32 v35, 0
	v_mov_b32_e32 v34, 0
	v_mov_b32_e32 v33, 0
	v_mov_b32_e32 v32, 0
	v_mov_b32_e32 v23, 0
	v_mov_b32_e32 v22, 0
	v_mov_b32_e32 v21, 0
	v_mov_b32_e32 v20, 0
	v_mov_b32_e32 v19, 0
	v_mov_b32_e32 v18, 0
	v_mov_b32_e32 v17, 0
	v_mov_b32_e32 v16, 0
	v_mov_b32_e32 v7, 0
	v_mov_b32_e32 v6, 0
	v_mov_b32_e32 v5, 0
	v_mov_b32_e32 v4, 0
	v_mov_b32_e32 v3, 0
	v_mov_b32_e32 v2, 0
	v_mov_b32_e32 v1, 0
	v_mov_b32_e32 v0, 0
	s_barrier
	s_cbranch_scc1 .LBB0_867
	s_ashr_i32 s52, s27, 31
	s_lshr_b32 s52, s52, 26
	s_add_i32 s27, s27, s52
	v_or_b32_e32 v0, s6, v130
	s_ashr_i32 s68, s27, 6
	v_lshlrev_b32_e32 v1, 4, v142
	v_lshlrev_b32_e32 v2, 6, v0
	s_movk_i32 s27, 0x3c0
	v_lshlrev_b32_e32 v0, 2, v0
	v_and_or_b32 v2, v2, s27, v1
	s_lshl_b32 s27, s70, 13
	v_and_b32_e32 v0, 32, v0
	v_bitop3_b32 v131, v2, s27, v0 bitop3:0xde
	v_lshl_or_b32 v0, v130, 6, v1
	v_lshlrev_b32_e32 v1, 2, v130
	s_lshl_b32 s27, s3, 7
	v_and_b32_e32 v1, 32, v1
	v_bitop3_b32 v2, v0, s27, v1 bitop3:0xde
	s_mov_b32 s27, s5
	s_add_i32 s69, s68, -2
	s_lshl_b64 s[26:27], s[26:27], 9
	s_add_u32 s26, s26, 0x10100
	s_addc_u32 s27, s27, 0
	s_mul_i32 s25, s26, s25
	s_mul_hi_u32 s52, s26, s24
	s_add_i32 s25, s52, s25
	s_mul_i32 s27, s27, s24
	s_add_i32 s25, s25, s27
	s_mul_i32 s26, s26, s24
	v_add_u32_e32 v0, v143, v138
	s_add_u32 s24, s64, s26
	v_add_lshl_u32 v0, v0, v139, 1
	v_mov_b32_e32 v1, 0
	s_addc_u32 s25, s65, s25
	v_lshl_add_u64 v[138:139], s[24:25], 0, v[0:1]
	v_add_u32_e32 v0, v141, v127
	v_add_lshl_u32 v0, v0, v140, 1
	v_lshl_add_u64 v[140:141], s[24:25], 0, v[0:1]
	v_or_b32_e32 v143, 0x10000, v2
	v_add_u32_e32 v144, 0x10400, v2
	v_add_u32_e32 v145, 0x10800, v2
	v_add_u32_e32 v146, 0x10c00, v2
	v_or_b32_e32 v147, 0x14000, v2
	v_add_u32_e32 v148, 0x14400, v2
	v_add_u32_e32 v149, 0x14800, v2
	v_add_u32_e32 v150, 0x14c00, v2
	s_add_i32 s70, s7, 0xc000
	s_add_i32 s71, s7, 0xe000
	v_or_b32_e32 v151, 0x18000, v2
	v_add_u32_e32 v152, 0x18400, v2
	v_add_u32_e32 v153, 0x18800, v2
	v_add_u32_e32 v154, 0x18c00, v2
	v_or_b32_e32 v155, 0x1c000, v2
	v_add_u32_e32 v156, 0x1c400, v2
	v_add_u32_e32 v157, 0x1c800, v2
	v_add_u32_e32 v158, 0x1cc00, v2
	s_mov_b64 s[24:25], 0x80
	s_mov_b32 s26, s5
	v_mov_b32_e32 v0, v1
	v_mov_b32_e32 v2, v1
	v_mov_b32_e32 v3, v1
	v_mov_b32_e32 v4, v1
	v_mov_b32_e32 v5, v1
	v_mov_b32_e32 v6, v1
	v_mov_b32_e32 v7, v1
	v_mov_b32_e32 v16, v1
	v_mov_b32_e32 v17, v1
	v_mov_b32_e32 v18, v1
	v_mov_b32_e32 v19, v1
	v_mov_b32_e32 v20, v1
	v_mov_b32_e32 v21, v1
	v_mov_b32_e32 v22, v1
	v_mov_b32_e32 v23, v1
	v_mov_b32_e32 v32, v1
	v_mov_b32_e32 v33, v1
	v_mov_b32_e32 v34, v1
	v_mov_b32_e32 v35, v1
	v_mov_b32_e32 v36, v1
	v_mov_b32_e32 v37, v1
	v_mov_b32_e32 v38, v1
	v_mov_b32_e32 v39, v1
	v_mov_b32_e32 v48, v1
	v_mov_b32_e32 v49, v1
	v_mov_b32_e32 v50, v1
	v_mov_b32_e32 v51, v1
	v_mov_b32_e32 v52, v1
	v_mov_b32_e32 v53, v1
	v_mov_b32_e32 v54, v1
	v_mov_b32_e32 v55, v1
	v_mov_b32_e32 v8, v1
	v_mov_b32_e32 v9, v1
	v_mov_b32_e32 v10, v1
	v_mov_b32_e32 v11, v1
	v_mov_b32_e32 v12, v1
	v_mov_b32_e32 v13, v1
	v_mov_b32_e32 v14, v1
	v_mov_b32_e32 v15, v1
	v_mov_b32_e32 v24, v1
	v_mov_b32_e32 v25, v1
	v_mov_b32_e32 v26, v1
	v_mov_b32_e32 v27, v1
	v_mov_b32_e32 v28, v1
	v_mov_b32_e32 v29, v1
	v_mov_b32_e32 v30, v1
	v_mov_b32_e32 v31, v1
	v_mov_b32_e32 v40, v1
	v_mov_b32_e32 v41, v1
	v_mov_b32_e32 v42, v1
	v_mov_b32_e32 v43, v1
	v_mov_b32_e32 v44, v1
	v_mov_b32_e32 v45, v1
	v_mov_b32_e32 v46, v1
	v_mov_b32_e32 v47, v1
	v_mov_b32_e32 v56, v1
	v_mov_b32_e32 v57, v1
	v_mov_b32_e32 v58, v1
	v_mov_b32_e32 v59, v1
	v_mov_b32_e32 v60, v1
	v_mov_b32_e32 v61, v1
	v_mov_b32_e32 v62, v1
	v_mov_b32_e32 v63, v1
	v_mov_b32_e32 v64, v1
	v_mov_b32_e32 v65, v1
	v_mov_b32_e32 v66, v1
	v_mov_b32_e32 v67, v1
	v_mov_b32_e32 v68, v1
	v_mov_b32_e32 v69, v1
	v_mov_b32_e32 v70, v1
	v_mov_b32_e32 v71, v1
	v_mov_b32_e32 v80, v1
	v_mov_b32_e32 v81, v1
	v_mov_b32_e32 v82, v1
	v_mov_b32_e32 v83, v1
	v_mov_b32_e32 v84, v1
	v_mov_b32_e32 v85, v1
	v_mov_b32_e32 v86, v1
	v_mov_b32_e32 v87, v1
	v_mov_b32_e32 v96, v1
	v_mov_b32_e32 v97, v1
	v_mov_b32_e32 v98, v1
	v_mov_b32_e32 v99, v1
	v_mov_b32_e32 v100, v1
	v_mov_b32_e32 v101, v1
	v_mov_b32_e32 v102, v1
	v_mov_b32_e32 v103, v1
	v_mov_b32_e32 v112, v1
	v_mov_b32_e32 v113, v1
	v_mov_b32_e32 v114, v1
	v_mov_b32_e32 v115, v1
	v_mov_b32_e32 v116, v1
	v_mov_b32_e32 v117, v1
	v_mov_b32_e32 v118, v1
	v_mov_b32_e32 v119, v1
	v_mov_b32_e32 v72, v1
	v_mov_b32_e32 v73, v1
	v_mov_b32_e32 v74, v1
	v_mov_b32_e32 v75, v1
	v_mov_b32_e32 v76, v1
	v_mov_b32_e32 v77, v1
	v_mov_b32_e32 v78, v1
	v_mov_b32_e32 v79, v1
	v_mov_b32_e32 v88, v1
	v_mov_b32_e32 v89, v1
	v_mov_b32_e32 v90, v1
	v_mov_b32_e32 v91, v1
	v_mov_b32_e32 v92, v1
	v_mov_b32_e32 v93, v1
	v_mov_b32_e32 v94, v1
	v_mov_b32_e32 v95, v1
	v_mov_b32_e32 v104, v1
	v_mov_b32_e32 v105, v1
	v_mov_b32_e32 v106, v1
	v_mov_b32_e32 v107, v1
	v_mov_b32_e32 v108, v1
	v_mov_b32_e32 v109, v1
	v_mov_b32_e32 v110, v1
	v_mov_b32_e32 v111, v1
	v_mov_b32_e32 v120, v1
	v_mov_b32_e32 v121, v1
	v_mov_b32_e32 v122, v1
	v_mov_b32_e32 v123, v1
	v_mov_b32_e32 v124, v1
	v_mov_b32_e32 v125, v1
	v_mov_b32_e32 v126, v1
	v_mov_b32_e32 v127, v1

.LBB0_873:
	s_lshl_b32 s16, s16, 5
	s_and_b32 s20, s16, 0x60
	s_add_i32 s35, s7, 0x18000
	s_mov_b64 s[16:17], 0xb80
	v_lshl_add_u64 v[0:1], v[0:1], 0, s[16:17]
	s_mov_b32 m0, s35
	s_add_i32 s36, s7, 0x1a000
	global_load_lds_dwordx4 v[0:1], off
	v_lshl_add_u64 v[0:1], v[6:7], 0, s[16:17]
	s_mov_b32 m0, s36
	s_add_i32 s37, s7, 0x8000
	global_load_lds_dwordx4 v[0:1], off
	v_lshl_add_u64 v[0:1], v[8:9], 0, s[16:17]
	s_mov_b32 m0, s37
	s_add_i32 s46, s7, 0xa000
	global_load_lds_dwordx4 v[0:1], off
	v_lshl_add_u64 v[0:1], v[10:11], 0, s[16:17]
	s_mov_b32 m0, s46
	s_add_i32 s47, s7, 0x1c000
	global_load_lds_dwordx4 v[0:1], off
	v_lshl_add_u64 v[0:1], v[2:3], 0, s[16:17]
	s_mov_b32 m0, s47
	s_add_i32 s48, s7, 0x1e000
	global_load_lds_dwordx4 v[0:1], off
	v_lshl_add_u64 v[0:1], v[4:5], 0, s[16:17]
	s_mov_b32 m0, s48
	s_lshl_b32 s6, s25, 6
	global_load_lds_dwordx4 v[0:1], off
	s_waitcnt vmcnt(8)
	s_mov_b32 s99, 0
	s_barrier
	s_waitcnt vmcnt(6)
	s_mov_b32 s5, 0
	v_and_b32_e32 v130, 15, v12
	v_bfe_u32 v142, v12, 4, 2
	s_cmp_lt_i32 s19, 64
	v_mov_b32_e32 v126, 0
	v_mov_b32_e32 v125, 0
	v_mov_b32_e32 v124, 0
	v_mov_b32_e32 v123, 0
	v_mov_b32_e32 v122, 0
	v_mov_b32_e32 v121, 0
	v_mov_b32_e32 v120, 0
	v_mov_b32_e32 v111, 0
	v_mov_b32_e32 v110, 0
	v_mov_b32_e32 v109, 0
	v_mov_b32_e32 v108, 0
	v_mov_b32_e32 v107, 0
	v_mov_b32_e32 v106, 0
	v_mov_b32_e32 v105, 0
	v_mov_b32_e32 v104, 0
	v_mov_b32_e32 v95, 0
	v_mov_b32_e32 v94, 0
	v_mov_b32_e32 v93, 0
	v_mov_b32_e32 v92, 0
	v_mov_b32_e32 v91, 0
	v_mov_b32_e32 v90, 0
	v_mov_b32_e32 v89, 0
	v_mov_b32_e32 v88, 0
	v_mov_b32_e32 v79, 0
	v_mov_b32_e32 v78, 0
	v_mov_b32_e32 v77, 0
	v_mov_b32_e32 v76, 0
	v_mov_b32_e32 v75, 0
	v_mov_b32_e32 v74, 0
	v_mov_b32_e32 v73, 0
	v_mov_b32_e32 v72, 0
	v_mov_b32_e32 v119, 0
	v_mov_b32_e32 v118, 0
	v_mov_b32_e32 v117, 0
	v_mov_b32_e32 v116, 0
	v_mov_b32_e32 v115, 0
	v_mov_b32_e32 v114, 0
	v_mov_b32_e32 v113, 0
	v_mov_b32_e32 v112, 0
	v_mov_b32_e32 v103, 0
	v_mov_b32_e32 v102, 0
	v_mov_b32_e32 v101, 0
	v_mov_b32_e32 v100, 0
	v_mov_b32_e32 v99, 0
	v_mov_b32_e32 v98, 0
	v_mov_b32_e32 v97, 0
	v_mov_b32_e32 v96, 0
	v_mov_b32_e32 v87, 0
	v_mov_b32_e32 v86, 0
	v_mov_b32_e32 v85, 0
	v_mov_b32_e32 v84, 0
	v_mov_b32_e32 v83, 0
	v_mov_b32_e32 v82, 0
	v_mov_b32_e32 v81, 0
	v_mov_b32_e32 v80, 0
	v_mov_b32_e32 v71, 0
	v_mov_b32_e32 v70, 0
	v_mov_b32_e32 v69, 0
	v_mov_b32_e32 v68, 0
	v_mov_b32_e32 v67, 0
	v_mov_b32_e32 v66, 0
	v_mov_b32_e32 v65, 0
	v_mov_b32_e32 v64, 0
	v_mov_b32_e32 v63, 0
	v_mov_b32_e32 v62, 0
	v_mov_b32_e32 v61, 0
	v_mov_b32_e32 v60, 0
	v_mov_b32_e32 v59, 0
	v_mov_b32_e32 v58, 0
	v_mov_b32_e32 v57, 0
	v_mov_b32_e32 v56, 0
	v_mov_b32_e32 v47, 0
	v_mov_b32_e32 v46, 0
	v_mov_b32_e32 v45, 0
	v_mov_b32_e32 v44, 0
	v_mov_b32_e32 v43, 0
	v_mov_b32_e32 v42, 0
	v_mov_b32_e32 v41, 0
	v_mov_b32_e32 v40, 0
	v_mov_b32_e32 v31, 0
	v_mov_b32_e32 v30, 0
	v_mov_b32_e32 v29, 0
	v_mov_b32_e32 v28, 0
	v_mov_b32_e32 v27, 0
	v_mov_b32_e32 v26, 0
	v_mov_b32_e32 v25, 0
	v_mov_b32_e32 v24, 0
	v_mov_b32_e32 v15, 0
	v_mov_b32_e32 v14, 0
	v_mov_b32_e32 v13, 0
	v_mov_b32_e32 v12, 0
	v_mov_b32_e32 v11, 0
	v_mov_b32_e32 v10, 0
	v_mov_b32_e32 v9, 0
	v_mov_b32_e32 v8, 0
	v_mov_b32_e32 v55, 0
	v_mov_b32_e32 v54, 0
	v_mov_b32_e32 v53, 0
	v_mov_b32_e32 v52, 0
	v_mov_b32_e32 v51, 0
	v_mov_b32_e32 v50, 0
	v_mov_b32_e32 v49, 0
	v_mov_b32_e32 v48, 0
	v_mov_b32_e32 v39, 0
	v_mov_b32_e32 v38, 0
	v_mov_b32_e32 v37, 0
	v_mov_b32_e32 v36, 0
	v_mov_b32_e32 v35, 0
	v_mov_b32_e32 v34, 0
	v_mov_b32_e32 v33, 0
	v_mov_b32_e32 v32, 0
	v_mov_b32_e32 v23, 0
	v_mov_b32_e32 v22, 0
	v_mov_b32_e32 v21, 0
	v_mov_b32_e32 v20, 0
	v_mov_b32_e32 v19, 0
	v_mov_b32_e32 v18, 0
	v_mov_b32_e32 v17, 0
	v_mov_b32_e32 v16, 0
	v_mov_b32_e32 v7, 0
	v_mov_b32_e32 v6, 0
	v_mov_b32_e32 v5, 0
	v_mov_b32_e32 v4, 0
	v_mov_b32_e32 v3, 0
	v_mov_b32_e32 v2, 0
	v_mov_b32_e32 v1, 0
	v_mov_b32_e32 v0, 0
	s_barrier
	s_cbranch_scc1 .LBB0_877
	s_ashr_i32 s26, s19, 31
	s_lshr_b32 s26, s26, 26
	v_or_b32_e32 v0, s6, v130
	s_add_i32 s19, s19, s26
	v_lshlrev_b32_e32 v1, 4, v142
	v_lshlrev_b32_e32 v2, 6, v0
	s_movk_i32 s26, 0x3c0
	v_lshlrev_b32_e32 v0, 2, v0
	v_and_or_b32 v2, v2, s26, v1
	s_lshl_b32 s25, s25, 13
	v_and_b32_e32 v0, 32, v0
	v_bitop3_b32 v131, v2, s25, v0 bitop3:0xde
	v_lshl_or_b32 v0, v130, 6, v1
	v_lshlrev_b32_e32 v1, 2, v130
	s_lshl_b32 s25, s20, 7
	v_and_b32_e32 v1, 32, v1
	s_ashr_i32 s19, s19, 6
	v_bitop3_b32 v2, v0, s25, v1 bitop3:0xde
	s_mov_b32 s25, s5
	s_add_i32 s49, s19, -2
	s_lshl_b64 s[24:25], s[24:25], 9
	s_add_u32 s24, s24, 0x10100
	s_addc_u32 s25, s25, 0
	s_mul_i32 s1, s24, s1
	s_mul_hi_u32 s26, s24, s0
	s_add_i32 s1, s26, s1
	s_mul_i32 s25, s25, s0
	s_add_i32 s1, s1, s25
	s_mul_i32 s24, s24, s0
	v_add_u32_e32 v0, v139, v127
	s_add_u32 s0, s64, s24
	v_add_lshl_u32 v0, v0, v138, 1
	v_mov_b32_e32 v1, 0
	s_addc_u32 s1, s65, s1
	v_lshl_add_u64 v[138:139], s[0:1], 0, v[0:1]
	v_add_u32_e32 v0, v143, v140
	v_add_lshl_u32 v0, v0, v141, 1
	v_lshl_add_u64 v[140:141], s[0:1], 0, v[0:1]
	v_or_b32_e32 v143, 0x10000, v2
	v_add_u32_e32 v144, 0x10400, v2
	v_add_u32_e32 v145, 0x10800, v2
	v_add_u32_e32 v146, 0x10c00, v2
	v_or_b32_e32 v147, 0x14000, v2
	v_add_u32_e32 v148, 0x14400, v2
	v_add_u32_e32 v149, 0x14800, v2
	v_add_u32_e32 v150, 0x14c00, v2
	s_add_i32 s68, s7, 0xc000
	s_add_i32 s69, s7, 0xe000
	s_mov_b64 s[0:1], 0xb00
	v_or_b32_e32 v151, 0x18000, v2
	v_add_u32_e32 v152, 0x18400, v2
	v_add_u32_e32 v153, 0x18800, v2
	v_add_u32_e32 v154, 0x18c00, v2
	v_or_b32_e32 v155, 0x1c000, v2
	v_add_u32_e32 v156, 0x1c400, v2
	v_add_u32_e32 v157, 0x1c800, v2
	v_add_u32_e32 v158, 0x1cc00, v2
	s_mov_b64 s[24:25], 0xb80
	s_mov_b32 s26, s5
	v_mov_b32_e32 v0, v1
	v_mov_b32_e32 v2, v1
	v_mov_b32_e32 v3, v1
	v_mov_b32_e32 v4, v1
	v_mov_b32_e32 v5, v1
	v_mov_b32_e32 v6, v1
	v_mov_b32_e32 v7, v1
	v_mov_b32_e32 v16, v1
	v_mov_b32_e32 v17, v1
	v_mov_b32_e32 v18, v1
	v_mov_b32_e32 v19, v1
	v_mov_b32_e32 v20, v1
	v_mov_b32_e32 v21, v1
	v_mov_b32_e32 v22, v1
	v_mov_b32_e32 v23, v1
	v_mov_b32_e32 v32, v1
	v_mov_b32_e32 v33, v1
	v_mov_b32_e32 v34, v1
	v_mov_b32_e32 v35, v1
	v_mov_b32_e32 v36, v1
	v_mov_b32_e32 v37, v1
	v_mov_b32_e32 v38, v1
	v_mov_b32_e32 v39, v1
	v_mov_b32_e32 v48, v1
	v_mov_b32_e32 v49, v1
	v_mov_b32_e32 v50, v1
	v_mov_b32_e32 v51, v1
	v_mov_b32_e32 v52, v1
	v_mov_b32_e32 v53, v1
	v_mov_b32_e32 v54, v1
	v_mov_b32_e32 v55, v1
	v_mov_b32_e32 v8, v1
	v_mov_b32_e32 v9, v1
	v_mov_b32_e32 v10, v1
	v_mov_b32_e32 v11, v1
	v_mov_b32_e32 v12, v1
	v_mov_b32_e32 v13, v1
	v_mov_b32_e32 v14, v1
	v_mov_b32_e32 v15, v1
	v_mov_b32_e32 v24, v1
	v_mov_b32_e32 v25, v1
	v_mov_b32_e32 v26, v1
	v_mov_b32_e32 v27, v1
	v_mov_b32_e32 v28, v1
	v_mov_b32_e32 v29, v1
	v_mov_b32_e32 v30, v1
	v_mov_b32_e32 v31, v1
	v_mov_b32_e32 v40, v1
	v_mov_b32_e32 v41, v1
	v_mov_b32_e32 v42, v1
	v_mov_b32_e32 v43, v1
	v_mov_b32_e32 v44, v1
	v_mov_b32_e32 v45, v1
	v_mov_b32_e32 v46, v1
	v_mov_b32_e32 v47, v1
	v_mov_b32_e32 v56, v1
	v_mov_b32_e32 v57, v1
	v_mov_b32_e32 v58, v1
	v_mov_b32_e32 v59, v1
	v_mov_b32_e32 v60, v1
	v_mov_b32_e32 v61, v1
	v_mov_b32_e32 v62, v1
	v_mov_b32_e32 v63, v1
	v_mov_b32_e32 v64, v1
	v_mov_b32_e32 v65, v1
	v_mov_b32_e32 v66, v1
	v_mov_b32_e32 v67, v1
	v_mov_b32_e32 v68, v1
	v_mov_b32_e32 v69, v1
	v_mov_b32_e32 v70, v1
	v_mov_b32_e32 v71, v1
	v_mov_b32_e32 v80, v1
	v_mov_b32_e32 v81, v1
	v_mov_b32_e32 v82, v1
	v_mov_b32_e32 v83, v1
	v_mov_b32_e32 v84, v1
	v_mov_b32_e32 v85, v1
	v_mov_b32_e32 v86, v1
	v_mov_b32_e32 v87, v1
	v_mov_b32_e32 v96, v1
	v_mov_b32_e32 v97, v1
	v_mov_b32_e32 v98, v1
	v_mov_b32_e32 v99, v1
	v_mov_b32_e32 v100, v1
	v_mov_b32_e32 v101, v1
	v_mov_b32_e32 v102, v1
	v_mov_b32_e32 v103, v1
	v_mov_b32_e32 v112, v1
	v_mov_b32_e32 v113, v1
	v_mov_b32_e32 v114, v1
	v_mov_b32_e32 v115, v1
	v_mov_b32_e32 v116, v1
	v_mov_b32_e32 v117, v1
	v_mov_b32_e32 v118, v1
	v_mov_b32_e32 v119, v1
	v_mov_b32_e32 v72, v1
	v_mov_b32_e32 v73, v1
	v_mov_b32_e32 v74, v1
	v_mov_b32_e32 v75, v1
	v_mov_b32_e32 v76, v1
	v_mov_b32_e32 v77, v1
	v_mov_b32_e32 v78, v1
	v_mov_b32_e32 v79, v1
	v_mov_b32_e32 v88, v1
	v_mov_b32_e32 v89, v1
	v_mov_b32_e32 v90, v1
	v_mov_b32_e32 v91, v1
	v_mov_b32_e32 v92, v1
	v_mov_b32_e32 v93, v1
	v_mov_b32_e32 v94, v1
	v_mov_b32_e32 v95, v1
	v_mov_b32_e32 v104, v1
	v_mov_b32_e32 v105, v1
	v_mov_b32_e32 v106, v1
	v_mov_b32_e32 v107, v1
	v_mov_b32_e32 v108, v1
	v_mov_b32_e32 v109, v1
	v_mov_b32_e32 v110, v1
	v_mov_b32_e32 v111, v1
	v_mov_b32_e32 v120, v1
	v_mov_b32_e32 v121, v1
	v_mov_b32_e32 v122, v1
	v_mov_b32_e32 v123, v1
	v_mov_b32_e32 v124, v1
	v_mov_b32_e32 v125, v1
	v_mov_b32_e32 v126, v1
	v_mov_b32_e32 v127, v1

.LBB0_1083:
	s_add_i32 s97, s3, 0x18000
	s_mov_b64 s[46:47], 0x80
	v_lshl_add_u64 v[8:9], v[8:9], 0, s[46:47]
	s_mov_b32 m0, s97
	s_add_i32 s96, s3, 0x1a000
	global_load_lds_dwordx4 v[8:9], off
	v_lshl_add_u64 v[4:5], v[4:5], 0, s[46:47]
	s_mov_b32 m0, s96
	s_add_i32 s20, s3, 0x8000
	global_load_lds_dwordx4 v[4:5], off
	v_lshl_add_u64 v[4:5], v[6:7], 0, s[46:47]
	s_mov_b32 m0, s20
	s_add_i32 s21, s3, 0xa000
	global_load_lds_dwordx4 v[4:5], off
	v_lshl_add_u64 v[4:5], v[10:11], 0, s[46:47]
	s_mov_b32 m0, s21
	s_add_i32 s90, s3, 0x1c000
	global_load_lds_dwordx4 v[4:5], off
	v_lshl_add_u64 v[2:3], v[2:3], 0, s[46:47]
	s_mov_b32 m0, s90
	s_add_i32 s28, s3, 0x1e000
	global_load_lds_dwordx4 v[2:3], off
	v_lshl_add_u64 v[0:1], v[0:1], 0, s[46:47]
	s_mov_b32 m0, s28
	s_ashr_i32 s4, s11, 31
	global_load_lds_dwordx4 v[0:1], off
	v_bfe_u32 v159, v12, 4, 2
	s_lshr_b32 s4, s4, 26
	v_and_b32_e32 v158, 15, v12
	s_add_i32 s4, s11, s4
	v_lshlrev_b32_e32 v0, 4, v159
	v_lshlrev_b32_e32 v1, 2, v12
	s_ashr_i32 s29, s4, 6
	v_lshl_or_b32 v0, v158, 6, v0
	s_lshl_b32 s4, s18, 13
	v_and_b32_e32 v1, 32, v1
	v_bitop3_b32 v160, v0, s4, v1 bitop3:0xde
	s_lshl_b32 s4, s19, 5
	s_and_b32 s34, s4, 0x60
	s_lshl_b32 s48, s18, 6
	s_lshl_b32 s4, s34, 7
	s_cmp_gt_i32 s11, 63
	s_cselect_b64 s[58:59], -1, 0
	s_add_i32 s35, s29, -2
	v_bitop3_b32 v2, v0, s4, v1 bitop3:0xde
	s_cmpk_lt_u32 s10, 0x100
	v_readlane_b32 s4, v246, 5
	s_cselect_b64 s[68:69], -1, 0
	s_ashr_i32 s49, s48, 31
	s_ashr_i32 s33, s4, 31
	s_ashr_i32 s37, s2, 31
	v_add_u32_e32 v0, v15, v13
	s_add_u32 s72, s64, 0xac40000
	v_add_lshl_u32 v0, v0, v14, 1
	v_mov_b32_e32 v1, v139
	s_waitcnt vmcnt(8)
	s_mov_b32 s99, 0
	s_barrier
	s_waitcnt vmcnt(6)
	v_readlane_b32 s5, v246, 6
	s_addc_u32 s73, s65, 0
	v_lshl_add_u64 v[144:145], s[0:1], 0, v[0:1]
	v_add_u32_e32 v0, v18, v16
	v_writelane_b32 v246, s56, 14
	s_add_u32 s74, s64, 0xaa00000
	v_add_lshl_u32 v0, v0, v17, 1
	v_writelane_b32 v246, s57, 15
	s_mov_b32 s71, 0
	s_mov_b32 s36, s4
	s_addc_u32 s75, s65, 0
	v_lshl_add_u64 v[146:147], s[0:1], 0, v[0:1]
	v_mov_b64_e32 v[148:149], 0x97f
	v_or_b32_e32 v161, 0x10000, v2
	v_add_u32_e32 v164, 0x10400, v2
	v_add_u32_e32 v165, 0x10800, v2
	v_add_u32_e32 v166, 0x10c00, v2
	v_or_b32_e32 v167, 0x14000, v2
	v_add_u32_e32 v168, 0x14400, v2
	v_add_u32_e32 v169, 0x14800, v2
	v_add_u32_e32 v170, 0x14c00, v2
	s_add_i32 s18, s3, 0xc000
	s_add_i32 s19, s3, 0xe000
	v_or_b32_e32 v171, 0x18000, v2
	v_add_u32_e32 v172, 0x18400, v2
	v_add_u32_e32 v173, 0x18800, v2
	v_add_u32_e32 v174, 0x18c00, v2
	v_or_b32_e32 v175, 0x1c000, v2
	v_add_u32_e32 v176, 0x1c400, v2
	v_add_u32_e32 v177, 0x1c800, v2
	v_add_u32_e32 v178, 0x1cc00, v2
	v_mbcnt_hi_u32_b32 v179, -1, v163
	v_mov_b32_e32 v180, 0x3e38aa3b
	s_mov_b32 s81, 0
	v_writelane_b32 v246, s58, 16
	s_barrier
	s_nop 0
	v_writelane_b32 v246, s59, 17
	s_branch .LBB0_1086

.LBB0_1210:
	s_add_i32 s34, s3, 0x18000
	s_mov_b64 s[66:67], 0x80
	v_lshl_add_u64 v[8:9], v[8:9], 0, s[66:67]
	s_mov_b32 m0, s34
	s_add_i32 s35, s3, 0x1a000
	global_load_lds_dwordx4 v[8:9], off
	v_lshl_add_u64 v[4:5], v[4:5], 0, s[66:67]
	s_mov_b32 m0, s35
	s_add_i32 s80, s3, 0x8000
	global_load_lds_dwordx4 v[4:5], off
	v_lshl_add_u64 v[4:5], v[6:7], 0, s[66:67]
	s_mov_b32 m0, s80
	s_add_i32 s81, s3, 0xa000
	global_load_lds_dwordx4 v[4:5], off
	v_lshl_add_u64 v[4:5], v[10:11], 0, s[66:67]
	s_mov_b32 m0, s81
	s_add_i32 s82, s3, 0x1c000
	global_load_lds_dwordx4 v[4:5], off
	v_lshl_add_u64 v[2:3], v[2:3], 0, s[66:67]
	s_mov_b32 m0, s82
	s_add_i32 s83, s3, 0x1e000
	global_load_lds_dwordx4 v[2:3], off
	v_lshl_add_u64 v[0:1], v[0:1], 0, s[66:67]
	s_mov_b32 m0, s83
	s_ashr_i32 s0, s15, 31
	global_load_lds_dwordx4 v[0:1], off
	v_bfe_u32 v153, v12, 4, 2
	s_lshr_b32 s0, s0, 26
	v_and_b32_e32 v152, 15, v12
	s_add_i32 s0, s15, s0
	v_lshlrev_b32_e32 v0, 4, v153
	v_lshlrev_b32_e32 v1, 2, v12
	s_ashr_i32 s84, s0, 6
	v_lshl_or_b32 v0, v152, 6, v0
	s_lshl_b32 s0, s6, 13
	v_and_b32_e32 v1, 32, v1
	v_bitop3_b32 v154, v0, s0, v1 bitop3:0xde
	s_lshl_b32 s0, s7, 5
	s_and_b32 s88, s0, 0x60
	s_lshl_b32 s0, s88, 7
	v_bitop3_b32 v2, v0, s0, v1 bitop3:0xde
	v_add_u32_e32 v0, v15, v13
	s_lshl_b32 s85, s6, 6
	v_add_lshl_u32 v0, v0, v14, 1
	v_mov_b32_e32 v1, v131
	s_cmp_gt_i32 s15, 63
	v_lshl_add_u64 v[136:137], s[26:27], 0, v[0:1]
	v_add_u32_e32 v0, v18, v16
	s_waitcnt vmcnt(8)
	s_mov_b32 s99, 0
	s_barrier
	s_waitcnt vmcnt(6)
	s_cselect_b64 s[0:1], -1, 0
	s_add_i32 s89, s84, -2
	v_readlane_b32 s4, v246, 5
	v_add_lshl_u32 v0, v0, v17, 1
	s_cmpk_lt_u32 s14, 0x100
	v_readlane_b32 s5, v246, 6
	v_lshl_add_u64 v[138:139], s[26:27], 0, v[0:1]
	v_cndmask_b32_e64 v0, 0, 1, s[0:1]
	s_cselect_b64 s[68:69], -1, 0
	s_ashr_i32 s90, s4, 31
	s_mov_b32 s91, s4
	s_ashr_i32 s92, s2, 31
	s_mov_b32 s93, 0
	v_mov_b64_e32 v[140:141], 0x180
	v_mov_b64_e32 v[142:143], 0x17f
	v_cmp_ne_u32_e64 s[4:5], 1, v0
	v_or_b32_e32 v155, 0x10000, v2
	v_add_u32_e32 v156, 0x10400, v2
	v_add_u32_e32 v157, 0x10800, v2
	v_add_u32_e32 v158, 0x10c00, v2
	v_or_b32_e32 v159, 0x14000, v2
	v_add_u32_e32 v160, 0x14400, v2
	v_add_u32_e32 v161, 0x14800, v2
	v_add_u32_e32 v164, 0x14c00, v2
	s_add_i32 s94, s3, 0xc000
	s_add_i32 s95, s3, 0xe000
	v_or_b32_e32 v165, 0x18000, v2
	v_add_u32_e32 v166, 0x18400, v2
	v_add_u32_e32 v167, 0x18800, v2
	v_add_u32_e32 v168, 0x18c00, v2
	v_or_b32_e32 v169, 0x1c000, v2
	v_add_u32_e32 v170, 0x1c400, v2
	v_add_u32_e32 v171, 0x1c800, v2
	v_add_u32_e32 v172, 0x1cc00, v2
	v_mov_b32_e32 v173, 0x358637bd
	s_mov_b32 s96, 0x800000
	s_movk_i32 s97, 0x600
	v_mbcnt_hi_u32_b32 v174, -1, v163
	s_barrier
	s_branch .LBB0_1213

.LBB0_1273:
	s_add_i32 s68, s21, 0x18000
	s_mov_b64 s[26:27], 0x80
	v_lshl_add_u64 v[8:9], v[8:9], 0, s[26:27]
	s_mov_b32 m0, s68
	s_add_i32 s69, s21, 0x1a000
	global_load_lds_dwordx4 v[8:9], off
	v_lshl_add_u64 v[4:5], v[4:5], 0, s[26:27]
	s_mov_b32 m0, s69
	s_add_i32 s70, s21, 0x8000
	global_load_lds_dwordx4 v[4:5], off
	v_lshl_add_u64 v[4:5], v[6:7], 0, s[26:27]
	s_mov_b32 m0, s70
	s_add_i32 s71, s21, 0xa000
	global_load_lds_dwordx4 v[4:5], off
	v_lshl_add_u64 v[4:5], v[10:11], 0, s[26:27]
	s_mov_b32 m0, s71
	s_add_i32 s72, s21, 0x1c000
	global_load_lds_dwordx4 v[4:5], off
	v_lshl_add_u64 v[2:3], v[2:3], 0, s[26:27]
	s_mov_b32 m0, s72
	s_add_i32 s73, s21, 0x1e000
	global_load_lds_dwordx4 v[2:3], off
	v_lshl_add_u64 v[0:1], v[0:1], 0, s[26:27]
	s_mov_b32 m0, s73
	s_ashr_i32 s6, s36, 31
	global_load_lds_dwordx4 v[0:1], off
	v_bfe_u32 v145, v12, 4, 2
	s_lshr_b32 s6, s6, 26
	v_and_b32_e32 v144, 15, v12
	s_add_i32 s6, s36, s6
	v_lshlrev_b32_e32 v0, 4, v145
	v_lshlrev_b32_e32 v1, 2, v12
	s_ashr_i32 s74, s6, 6
	v_lshl_or_b32 v0, v144, 6, v0
	s_lshl_b32 s6, s37, 13
	v_and_b32_e32 v1, 32, v1
	v_bitop3_b32 v146, v0, s6, v1 bitop3:0xde
	s_lshl_b32 s6, s43, 5
	s_and_b32 s8, s6, 0x60
	s_lshl_b32 s75, s37, 6
	s_lshl_b32 s6, s8, 7
	v_bitop3_b32 v2, v0, s6, v1 bitop3:0xde
	s_cmp_gt_i32 s36, 63
	v_add_u32_e32 v0, v15, v13
	s_cselect_b64 s[6:7], -1, 0
	s_cmpk_lt_i32 s2, 0x80
	v_add_lshl_u32 v0, v0, v14, 1
	v_mov_b32_e32 v1, v131
	s_cselect_b64 s[36:37], -1, 0
	s_lshl_b32 s76, s2, 2
	v_lshl_add_u64 v[136:137], s[0:1], 0, v[0:1]
	v_add_u32_e32 v0, v18, v16
	s_waitcnt vmcnt(8)
	s_mov_b32 s99, 0
	s_barrier
	s_waitcnt vmcnt(6)
	s_addk_i32 s76, 0xfe00
	s_add_i32 s77, s74, -2
	v_add_lshl_u32 v0, v0, v17, 1
	s_cmpk_lt_u32 s42, 0x100
	s_mov_b32 s47, 0
	v_lshl_add_u64 v[138:139], s[0:1], 0, v[0:1]
	v_cndmask_b32_e64 v0, 0, 1, s[6:7]
	s_cselect_b64 s[42:43], -1, 0
	v_cmp_ne_u32_e64 s[6:7], 1, v0
	v_or_b32_e32 v147, 0x10000, v2
	v_add_u32_e32 v148, 0x10400, v2
	v_add_u32_e32 v149, 0x10800, v2
	v_add_u32_e32 v150, 0x10c00, v2
	v_or_b32_e32 v151, 0x14000, v2
	v_add_u32_e32 v152, 0x14400, v2
	v_add_u32_e32 v153, 0x14800, v2
	v_add_u32_e32 v154, 0x14c00, v2
	s_add_i32 s80, s21, 0xc000
	s_add_i32 s81, s21, 0xe000
	v_or_b32_e32 v155, 0x18000, v2
	v_add_u32_e32 v156, 0x18400, v2
	v_add_u32_e32 v157, 0x18800, v2
	v_add_u32_e32 v158, 0x18c00, v2
	v_or_b32_e32 v159, 0x1c000, v2
	v_add_u32_e32 v160, 0x1c400, v2
	v_add_u32_e32 v161, 0x1c800, v2
	v_add_u32_e32 v164, 0x1cc00, v2
	v_mov_b32_e32 v165, 0x358637bd
	s_mov_b32 s82, 0x800000
	s_lshl_b32 s46, s8, 1
	s_mov_b32 s51, s47
	s_barrier
	s_branch .LBB0_1276

.LBB0_1469:
	s_add_i32 s78, s21, 0x18000
	s_mov_b64 s[26:27], 0x80
	v_lshl_add_u64 v[8:9], v[8:9], 0, s[26:27]
	s_mov_b32 m0, s78
	s_add_i32 s79, s21, 0x1a000
	global_load_lds_dwordx4 v[8:9], off
	v_lshl_add_u64 v[4:5], v[4:5], 0, s[26:27]
	s_mov_b32 m0, s79
	s_add_i32 s85, s21, 0x8000
	global_load_lds_dwordx4 v[4:5], off
	v_lshl_add_u64 v[4:5], v[6:7], 0, s[26:27]
	s_mov_b32 m0, s85
	s_add_i32 s88, s21, 0xa000
	global_load_lds_dwordx4 v[4:5], off
	v_lshl_add_u64 v[4:5], v[10:11], 0, s[26:27]
	s_mov_b32 m0, s88
	s_add_i32 s89, s21, 0x1c000
	global_load_lds_dwordx4 v[4:5], off
	v_lshl_add_u64 v[2:3], v[2:3], 0, s[26:27]
	s_mov_b32 m0, s89
	s_add_i32 s90, s21, 0x1e000
	global_load_lds_dwordx4 v[2:3], off
	v_lshl_add_u64 v[0:1], v[0:1], 0, s[26:27]
	s_mov_b32 m0, s90
	s_ashr_i32 s0, s37, 31
	global_load_lds_dwordx4 v[0:1], off
	v_bfe_u32 v149, v12, 4, 2
	s_lshr_b32 s0, s0, 26
	v_and_b32_e32 v148, 15, v12
	s_add_i32 s0, s37, s0
	v_lshlrev_b32_e32 v0, 4, v149
	v_lshlrev_b32_e32 v1, 2, v12
	s_ashr_i32 s68, s0, 6
	v_lshl_or_b32 v0, v148, 6, v0
	s_lshl_b32 s0, s7, 13
	v_and_b32_e32 v1, 32, v1
	v_bitop3_b32 v150, v0, s0, v1 bitop3:0xde
	s_lshl_b32 s0, s42, 5
	s_and_b32 s70, s0, 0x60
	s_lshl_b32 s0, s70, 7
	v_bitop3_b32 v2, v0, s0, v1 bitop3:0xde
	v_add_u32_e32 v0, v15, v13
	s_lshl_b32 s69, s7, 6
	v_add_lshl_u32 v0, v0, v14, 1
	v_mov_b32_e32 v1, v131
	s_cmp_gt_i32 s37, 63
	v_lshl_add_u64 v[136:137], s[10:11], 0, v[0:1]
	v_add_u32_e32 v0, v18, v16
	s_waitcnt vmcnt(8)
	s_mov_b32 s99, 0
	s_barrier
	s_waitcnt vmcnt(6)
	s_cselect_b64 s[0:1], -1, 0
	s_add_i32 s71, s68, -2
	v_readlane_b32 s4, v246, 5
	v_add_lshl_u32 v0, v0, v17, 1
	s_cmpk_lt_u32 s36, 0x100
	v_readlane_b32 s5, v246, 6
	v_lshl_add_u64 v[138:139], s[10:11], 0, v[0:1]
	v_cndmask_b32_e64 v0, 0, 1, s[0:1]
	s_sext_i32_i8 s82, s6
	s_cselect_b64 s[36:37], -1, 0
	s_ashr_i32 s72, s69, 31
	s_ashr_i32 s73, s4, 31
	s_mov_b32 s74, s4
	s_mov_b32 s75, 0
	v_mov_b64_e32 v[140:141], 0x200
	v_mov_b64_e32 v[142:143], 0x1ff
	v_cmp_ne_u32_e64 s[4:5], 1, v0
	v_or_b32_e32 v151, 0x10000, v2
	v_add_u32_e32 v152, 0x10400, v2
	v_add_u32_e32 v153, 0x10800, v2
	v_add_u32_e32 v154, 0x10c00, v2
	v_or_b32_e32 v155, 0x14000, v2
	v_add_u32_e32 v156, 0x14400, v2
	v_add_u32_e32 v157, 0x14800, v2
	v_add_u32_e32 v158, 0x14c00, v2
	s_add_i32 s76, s21, 0xc000
	s_add_i32 s77, s21, 0xe000
	v_or_b32_e32 v159, 0x18000, v2
	v_add_u32_e32 v160, 0x18400, v2
	v_add_u32_e32 v161, 0x18800, v2
	v_add_u32_e32 v164, 0x18c00, v2
	v_or_b32_e32 v165, 0x1c000, v2
	v_add_u32_e32 v166, 0x1c400, v2
	v_add_u32_e32 v167, 0x1c800, v2
	v_add_u32_e32 v168, 0x1cc00, v2
	s_barrier
	s_branch .LBB0_1472

.LBB0_1498:
	s_add_i32 s35, s20, 0x18000
	s_mov_b64 s[24:25], 0x80
	v_lshl_add_u64 v[8:9], v[8:9], 0, s[24:25]
	s_mov_b32 m0, s35
	s_add_i32 s78, s20, 0x1a000
	global_load_lds_dwordx4 v[8:9], off
	v_lshl_add_u64 v[4:5], v[4:5], 0, s[24:25]
	s_mov_b32 m0, s78
	s_add_i32 s79, s20, 0x8000
	global_load_lds_dwordx4 v[4:5], off
	v_lshl_add_u64 v[4:5], v[6:7], 0, s[24:25]
	s_mov_b32 m0, s79
	s_add_i32 s82, s20, 0xa000
	global_load_lds_dwordx4 v[4:5], off
	v_lshl_add_u64 v[4:5], v[10:11], 0, s[24:25]
	s_mov_b32 m0, s82
	s_add_i32 s83, s20, 0x1c000
	global_load_lds_dwordx4 v[4:5], off
	v_lshl_add_u64 v[2:3], v[2:3], 0, s[24:25]
	s_mov_b32 m0, s83
	s_add_i32 s84, s20, 0x1e000
	global_load_lds_dwordx4 v[2:3], off
	v_lshl_add_u64 v[0:1], v[0:1], 0, s[24:25]
	s_mov_b32 m0, s84
	s_ashr_i32 s0, s7, 31
	global_load_lds_dwordx4 v[0:1], off
	v_bfe_u32 v149, v12, 4, 2
	s_lshr_b32 s0, s0, 26
	v_and_b32_e32 v148, 15, v12
	s_add_i32 s0, s7, s0
	v_lshlrev_b32_e32 v0, 4, v149
	v_lshlrev_b32_e32 v1, 2, v12
	s_ashr_i32 s85, s0, 6
	v_lshl_or_b32 v0, v148, 6, v0
	s_lshl_b32 s0, s5, 13
	v_and_b32_e32 v1, 32, v1
	v_bitop3_b32 v150, v0, s0, v1 bitop3:0xde
	s_lshl_b32 s0, s26, 5
	s_and_b32 s89, s0, 0x60
	s_lshl_b32 s0, s89, 7
	v_bitop3_b32 v2, v0, s0, v1 bitop3:0xde
	v_add_u32_e32 v0, v15, v13
	s_lshl_b32 s88, s5, 6
	v_add_lshl_u32 v0, v0, v14, 1
	v_mov_b32_e32 v1, v131
	s_cmp_gt_i32 s7, 63
	v_lshl_add_u64 v[136:137], s[10:11], 0, v[0:1]
	v_add_u32_e32 v0, v18, v16
	s_sext_i32_i8 s77, s4
	s_waitcnt vmcnt(8)
	s_mov_b32 s99, 0
	s_barrier
	s_waitcnt vmcnt(6)
	s_cselect_b64 s[0:1], -1, 0
	s_add_i32 s68, s85, -2
	v_readlane_b32 s4, v246, 5
	v_add_lshl_u32 v0, v0, v17, 1
	s_cmpk_lt_u32 s6, 0x100
	v_readlane_b32 s5, v246, 6
	v_lshl_add_u64 v[138:139], s[10:11], 0, v[0:1]
	v_cndmask_b32_e64 v0, 0, 1, s[0:1]
	s_cselect_b64 s[26:27], -1, 0
	s_ashr_i32 s69, s88, 31
	s_ashr_i32 s70, s4, 31
	s_mov_b32 s71, s4
	s_mov_b32 s72, 0
	v_mov_b64_e32 v[140:141], 0x200
	v_mov_b64_e32 v[142:143], 0x1ff
	v_cmp_ne_u32_e64 s[4:5], 1, v0
	v_or_b32_e32 v151, 0x10000, v2
	v_add_u32_e32 v152, 0x10400, v2
	v_add_u32_e32 v153, 0x10800, v2
	v_add_u32_e32 v154, 0x10c00, v2
	v_or_b32_e32 v155, 0x14000, v2
	v_add_u32_e32 v156, 0x14400, v2
	v_add_u32_e32 v157, 0x14800, v2
	v_add_u32_e32 v158, 0x14c00, v2
	s_add_i32 s73, s20, 0xc000
	s_add_i32 s74, s20, 0xe000
	v_or_b32_e32 v159, 0x18000, v2
	v_add_u32_e32 v160, 0x18400, v2
	v_add_u32_e32 v161, 0x18800, v2
	v_add_u32_e32 v164, 0x18c00, v2
	v_or_b32_e32 v165, 0x1c000, v2
	v_add_u32_e32 v166, 0x1c400, v2
	v_add_u32_e32 v167, 0x1c800, v2
	v_add_u32_e32 v168, 0x1cc00, v2
	s_mov_b64 s[36:37], 0xb0
	s_barrier
	s_branch .LBB0_1501

.LBB0_1581:
	s_add_i32 s34, s3, 0x18000
	s_mov_b64 s[26:27], 0x80
	v_lshl_add_u64 v[8:9], v[8:9], 0, s[26:27]
	s_mov_b32 m0, s34
	s_add_i32 s35, s3, 0x1a000
	global_load_lds_dwordx4 v[8:9], off
	v_lshl_add_u64 v[4:5], v[4:5], 0, s[26:27]
	s_mov_b32 m0, s35
	s_add_i32 s84, s3, 0x8000
	global_load_lds_dwordx4 v[4:5], off
	v_lshl_add_u64 v[4:5], v[6:7], 0, s[26:27]
	s_mov_b32 m0, s84
	s_add_i32 s85, s3, 0xa000
	global_load_lds_dwordx4 v[4:5], off
	v_lshl_add_u64 v[4:5], v[10:11], 0, s[26:27]
	s_mov_b32 m0, s85
	s_add_i32 s88, s3, 0x1c000
	global_load_lds_dwordx4 v[4:5], off
	v_lshl_add_u64 v[2:3], v[2:3], 0, s[26:27]
	s_mov_b32 m0, s88
	s_add_i32 s89, s3, 0x1e000
	global_load_lds_dwordx4 v[2:3], off
	v_lshl_add_u64 v[0:1], v[0:1], 0, s[26:27]
	s_mov_b32 m0, s89
	s_ashr_i32 s0, s37, 31
	global_load_lds_dwordx4 v[0:1], off
	v_bfe_u32 v149, v12, 4, 2
	s_lshr_b32 s0, s0, 26
	v_and_b32_e32 v148, 15, v12
	s_add_i32 s0, s37, s0
	v_lshlrev_b32_e32 v0, 4, v149
	v_lshlrev_b32_e32 v1, 2, v12
	s_ashr_i32 s90, s0, 6
	v_lshl_or_b32 v0, v148, 6, v0
	s_lshl_b32 s0, s6, 13
	v_and_b32_e32 v1, 32, v1
	v_bitop3_b32 v150, v0, s0, v1 bitop3:0xde
	s_lshl_b32 s0, s7, 5
	s_lshl_b32 s91, s6, 6
	s_and_b32 s6, s0, 0x60
	s_lshl_b32 s0, s6, 7
	v_bitop3_b32 v2, v0, s0, v1 bitop3:0xde
	v_add_u32_e32 v0, v15, v13
	v_add_lshl_u32 v0, v0, v14, 1
	v_mov_b32_e32 v1, v131
	s_cmp_gt_i32 s37, 63
	v_lshl_add_u64 v[136:137], s[12:13], 0, v[0:1]
	v_add_u32_e32 v0, v18, v16
	s_waitcnt vmcnt(8)
	s_mov_b32 s99, 0
	s_barrier
	s_waitcnt vmcnt(6)
	s_cselect_b64 s[0:1], -1, 0
	s_add_i32 s68, s90, -2
	v_readlane_b32 s4, v246, 5
	v_add_lshl_u32 v0, v0, v17, 1
	s_cmpk_lt_u32 s36, 0x100
	s_mov_b32 s43, 0
	v_readlane_b32 s5, v246, 6
	v_lshl_add_u64 v[138:139], s[12:13], 0, v[0:1]
	v_cndmask_b32_e64 v0, 0, 1, s[0:1]
	v_readlane_b32 s64, v246, 12
	s_cselect_b64 s[36:37], -1, 0
	s_ashr_i32 s69, s91, 31
	s_ashr_i32 s70, s4, 31
	s_mov_b32 s71, s4
	s_ashr_i32 s72, s2, 31
	v_mov_b64_e32 v[140:141], 0x200
	v_mov_b64_e32 v[142:143], 0x1ff
	v_cmp_ne_u32_e64 s[4:5], 1, v0
	v_or_b32_e32 v151, 0x10000, v2
	v_add_u32_e32 v152, 0x10400, v2
	v_add_u32_e32 v153, 0x10800, v2
	v_add_u32_e32 v154, 0x10c00, v2
	v_or_b32_e32 v155, 0x14000, v2
	v_add_u32_e32 v156, 0x14400, v2
	v_add_u32_e32 v157, 0x14800, v2
	v_add_u32_e32 v158, 0x14c00, v2
	s_add_i32 s73, s3, 0xc000
	s_add_i32 s74, s3, 0xe000
	v_or_b32_e32 v159, 0x18000, v2
	v_add_u32_e32 v160, 0x18400, v2
	v_add_u32_e32 v161, 0x18800, v2
	v_add_u32_e32 v164, 0x18c00, v2
	v_or_b32_e32 v165, 0x1c000, v2
	v_add_u32_e32 v166, 0x1c400, v2
	v_add_u32_e32 v167, 0x1c800, v2
	v_add_u32_e32 v168, 0x1cc00, v2
	v_mbcnt_hi_u32_b32 v169, -1, v163
	s_lshl_b32 s42, s6, 1
	s_mov_b64 s[46:47], 0xb0
	s_mov_b32 s75, s43
	v_readlane_b32 s65, v246, 13
	s_barrier
	s_branch .LBB0_1584

.LBB0_1738:
	s_add_i32 s51, s3, 0x18000
	s_mov_b64 s[24:25], 0x80
	v_lshl_add_u64 v[6:7], v[6:7], 0, s[24:25]
	s_mov_b32 m0, s51
	s_add_i32 s81, s3, 0x1a000
	global_load_lds_dwordx4 v[6:7], off
	v_lshl_add_u64 v[4:5], v[4:5], 0, s[24:25]
	s_mov_b32 m0, s81
	s_add_i32 s84, s3, 0x8000
	global_load_lds_dwordx4 v[4:5], off
	v_lshl_add_u64 v[4:5], v[8:9], 0, s[24:25]
	s_mov_b32 m0, s84
	s_add_i32 s85, s3, 0xa000
	global_load_lds_dwordx4 v[4:5], off
	v_lshl_add_u64 v[4:5], v[10:11], 0, s[24:25]
	s_mov_b32 m0, s85
	s_add_i32 s88, s3, 0x1c000
	global_load_lds_dwordx4 v[4:5], off
	v_lshl_add_u64 v[2:3], v[2:3], 0, s[24:25]
	s_mov_b32 m0, s88
	s_add_i32 s89, s3, 0x1e000
	global_load_lds_dwordx4 v[2:3], off
	v_lshl_add_u64 v[0:1], v[0:1], 0, s[24:25]
	s_mov_b32 m0, s89
	s_sext_i32_i8 s78, s0
	global_load_lds_dwordx4 v[0:1], off
	s_ashr_i32 s0, s16, 31
	v_bfe_u32 v145, v12, 4, 2
	s_lshr_b32 s0, s0, 26
	v_and_b32_e32 v144, 15, v12
	s_add_i32 s0, s16, s0
	v_lshlrev_b32_e32 v0, 4, v145
	v_lshlrev_b32_e32 v1, 2, v12
	s_ashr_i32 s91, s0, 6
	v_lshl_or_b32 v0, v144, 6, v0
	s_lshl_b32 s0, s27, 13
	v_and_b32_e32 v1, 32, v1
	v_bitop3_b32 v146, v0, s0, v1 bitop3:0xde
	s_lshl_b32 s0, s26, 5
	s_and_b32 s0, s0, 0x60
	s_lshl_b32 s4, s0, 7
	v_bitop3_b32 v2, v0, s4, v1 bitop3:0xde
	v_add_u32_e32 v0, v18, v16
	s_lshl_b32 s92, s27, 6
	v_add_lshl_u32 v0, v0, v17, 1
	v_mov_b32_e32 v1, v133
	s_cmp_gt_i32 s16, 63
	v_lshl_add_u64 v[136:137], s[8:9], 0, v[0:1]
	v_add_u32_e32 v0, v15, v13
	s_waitcnt vmcnt(8)
	s_mov_b32 s99, 0
	s_barrier
	s_waitcnt vmcnt(6)
	s_cselect_b64 s[4:5], -1, 0
	s_add_i32 s96, s91, -2
	v_add_lshl_u32 v0, v0, v14, 1
	s_cmpk_lt_u32 s1, 0x100
	v_readlane_b32 s6, v246, 5
	v_lshl_add_u64 v[138:139], s[8:9], 0, v[0:1]
	v_cndmask_b32_e64 v0, 0, 1, s[4:5]
	s_cselect_b64 s[26:27], -1, 0
	s_ashr_i32 s97, s92, 31
	s_ashr_i32 s94, s6, 31
	s_mov_b32 s95, s6
	v_mov_b64_e32 v[140:141], 0xb00
	v_mov_b64_e32 v[142:143], 0xaff
	v_cmp_ne_u32_e64 s[4:5], 1, v0
	v_or_b32_e32 v147, 0x10000, v2
	v_add_u32_e32 v148, 0x10400, v2
	v_add_u32_e32 v149, 0x10800, v2
	v_add_u32_e32 v150, 0x10c00, v2
	v_or_b32_e32 v151, 0x14000, v2
	v_add_u32_e32 v152, 0x14400, v2
	v_add_u32_e32 v153, 0x14800, v2
	v_add_u32_e32 v154, 0x14c00, v2
	s_add_i32 s90, s3, 0xc000
	s_add_i32 s68, s3, 0xe000
	v_or_b32_e32 v155, 0x18000, v2
	v_add_u32_e32 v156, 0x18400, v2
	v_add_u32_e32 v157, 0x18800, v2
	v_add_u32_e32 v158, 0x18c00, v2
	v_or_b32_e32 v159, 0x1c000, v2
	v_add_u32_e32 v160, 0x1c400, v2
	v_add_u32_e32 v161, 0x1c800, v2
	v_add_u32_e32 v164, 0x1cc00, v2
	s_movk_i32 s69, 0x1600
	s_lshl_b32 s16, s0, 1
	s_mov_b32 s70, 0x2c000
	s_mov_b32 s71, 0x42000
	s_mov_b32 s72, 0xb0000
	s_mov_b32 s73, 0xc6000
	s_mov_b32 s74, 0xdc000
	s_mov_b32 s75, s17
	s_barrier
	v_readlane_b32 s7, v246, 6
	s_branch .LBB0_1741

.LBB0_1817:
	s_add_i32 s84, s3, 0x18000
	s_mov_b64 s[20:21], 0x80
	v_lshl_add_u64 v[8:9], v[8:9], 0, s[20:21]
	s_mov_b32 m0, s84
	s_add_i32 s85, s3, 0x1a000
	global_load_lds_dwordx4 v[8:9], off
	v_lshl_add_u64 v[4:5], v[4:5], 0, s[20:21]
	s_mov_b32 m0, s85
	s_add_i32 s86, s3, 0x8000
	global_load_lds_dwordx4 v[4:5], off
	v_lshl_add_u64 v[4:5], v[6:7], 0, s[20:21]
	s_mov_b32 m0, s86
	s_add_i32 s87, s3, 0xa000
	global_load_lds_dwordx4 v[4:5], off
	v_lshl_add_u64 v[4:5], v[10:11], 0, s[20:21]
	s_mov_b32 m0, s87
	s_add_i32 s88, s3, 0x1c000
	global_load_lds_dwordx4 v[4:5], off
	v_lshl_add_u64 v[2:3], v[2:3], 0, s[20:21]
	s_mov_b32 m0, s88
	s_add_i32 s89, s3, 0x1e000
	global_load_lds_dwordx4 v[2:3], off
	v_lshl_add_u64 v[0:1], v[0:1], 0, s[20:21]
	s_mov_b32 m0, s89
	s_ashr_i32 s0, s25, 31
	global_load_lds_dwordx4 v[0:1], off
	v_bfe_u32 v149, v12, 4, 2
	s_lshr_b32 s0, s0, 26
	v_and_b32_e32 v148, 15, v12
	s_add_i32 s0, s25, s0
	v_lshlrev_b32_e32 v0, 4, v149
	v_lshlrev_b32_e32 v1, 2, v12
	s_ashr_i32 s90, s0, 6
	v_lshl_or_b32 v0, v148, 6, v0
	s_lshl_b32 s0, s6, 13
	v_and_b32_e32 v1, 32, v1
	v_bitop3_b32 v150, v0, s0, v1 bitop3:0xde
	s_lshl_b32 s0, s7, 5
	s_and_b32 s4, s0, 0x60
	s_lshl_b32 s0, s4, 7
	v_bitop3_b32 v2, v0, s0, v1 bitop3:0xde
	v_add_u32_e32 v0, v15, v13
	s_lshl_b32 s91, s6, 6
	v_add_lshl_u32 v0, v0, v14, 1
	v_mov_b32_e32 v1, v131
	s_cmp_gt_i32 s25, 63
	v_lshl_add_u64 v[136:137], s[10:11], 0, v[0:1]
	v_add_u32_e32 v0, v18, v16
	s_waitcnt vmcnt(8)
	s_mov_b32 s99, 0
	s_barrier
	s_waitcnt vmcnt(6)
	s_cselect_b64 s[0:1], -1, 0
	s_add_i32 s92, s90, -2
	v_readlane_b32 s6, v246, 5
	v_add_lshl_u32 v0, v0, v17, 1
	s_cmpk_lt_u32 s24, 0x100
	s_mov_b32 s27, 0
	v_readlane_b32 s7, v246, 6
	v_lshl_add_u64 v[138:139], s[10:11], 0, v[0:1]
	v_cndmask_b32_e64 v0, 0, 1, s[0:1]
	s_cselect_b64 s[24:25], -1, 0
	s_ashr_i32 s94, s91, 31
	s_ashr_i32 s68, s6, 31
	s_mov_b32 s69, s6
	s_ashr_i32 s70, s2, 31
	v_mov_b64_e32 v[140:141], 0x200
	v_mov_b64_e32 v[142:143], 0x1ff
	v_cmp_ne_u32_e64 s[6:7], 1, v0
	v_or_b32_e32 v151, 0x10000, v2
	v_add_u32_e32 v152, 0x10400, v2
	v_add_u32_e32 v153, 0x10800, v2
	v_add_u32_e32 v154, 0x10c00, v2
	v_or_b32_e32 v155, 0x14000, v2
	v_add_u32_e32 v156, 0x14400, v2
	v_add_u32_e32 v157, 0x14800, v2
	v_add_u32_e32 v158, 0x14c00, v2
	s_add_i32 s71, s3, 0xc000
	s_add_i32 s72, s3, 0xe000
	v_or_b32_e32 v159, 0x18000, v2
	v_add_u32_e32 v160, 0x18400, v2
	v_add_u32_e32 v161, 0x18800, v2
	v_add_u32_e32 v164, 0x18c00, v2
	v_or_b32_e32 v165, 0x1c000, v2
	v_add_u32_e32 v166, 0x1c400, v2
	v_add_u32_e32 v167, 0x1c800, v2
	v_add_u32_e32 v168, 0x1cc00, v2
	v_mbcnt_hi_u32_b32 v163, -1, v163
	s_lshl_b32 s26, s4, 1
	s_mov_b64 s[36:37], 0x90
	s_mov_b64 s[42:43], 0xa0
	s_mov_b64 s[46:47], 0xb0
	s_mov_b32 s73, s27
	s_barrier
	s_branch .LBB0_1820
